# P9 GLA scan rewritten by hand: 2 chunks per barrier, V and decay staged through LDS by LDS-DMA, K/Q prefetched 4 pairs ahead, transposed read-out MFMA with one dwordx2 store
# baseline (speedup 1.0000x reference)
; #define LAS __attribute__((address_space(3)))
; template <bool RO>
; __device__ __forceinline__ void p9_job(LAS unsigned char* lds, const bf16_t* __restrict__ kap, const bf16_t* __restrict__ vbp, const float* __restrict__ dcp, const bf16_t* __restrict__ qap, bf16_t* __restrict__ op, int wave, int c16, int kq) {
;     constexpr int PD = P9_DEPTH, NCT = P9_NCT;
;     f32x4 S[NCT];
; #pragma unroll
;     for (int ct = 0; ct < NCT; ++ct) S[ct] = (f32x4){0.f, 0.f, 0.f, 0.f};
;     bf16x8 ka[PD][2], vb[PD][NCT][2], qa[PD][4]; f32x4 dc[PD];
;     ...
; #pragma unroll
;     for (int u = 0; u < PD; ++u) P9_LOAD(u, u);
; __global__ void __launch_bounds__(512, 2) hybrid_fwd(Args args) {
;     ...
;     if (IN(9)) {
;         PH_IDS
;         for (int jb = blk; jb < 16 * (16 / P9_NCT); jb += G) {
;             constexpr int JPB = 16 / P9_NCT;
;             const int idx = jb >> 3, bh = 2 * (jb & 7) + idx / JPB, dvs = idx % JPB;
;             const int b = bh >> 2, h = bh & 3;
;             const int c16 = lane & 15, kq = lane >> 4;
;             const bf16_t* kap = KDT + (size_t)(b * 4 + h) * 128 * 8192 + wave * 1024 + lane * 8;
;             const bf16_t* vbp = VT + (size_t)(b * 4 + h) * 128 * 16384 + dvs * P9_NCT * 1024 + lane * 8;
;             const float* dcp = DEC + (size_t)(b * 128) * 512 + h * 128 + 16 * wave + 4 * kq;
;             const bf16_t* qap = Qb + (size_t)(b * 4 + h) * 128 * 8192 + (wave & 3) * 2048 + lane * 8;
;             bf16_t* op = Ob + ((size_t)b * SEQ + 16 * (wave & 3) + 4 * kq) * 1024 + h * 256 + dvs * 16 * P9_NCT + c16;
;             if (wave < 4) p9_job<true>(lds, kap, vbp, dcp, qap, op, wave, c16, kq);
;             else p9_job<false>(lds, kap, vbp, dcp, qap, op, wave, c16, kq);
.LBB0_1038:
	s_cmp_lt_i32 s82, 10
	s_cselect_b64 s[8:9], -1, 0
	s_and_b64 s[6:7], s[8:9], s[6:7]
	s_andn2_b64 vcc, exec, s[6:7]
	s_cbranch_vccnz .LBB0_1049
	v_mov_b32_e32 v0, v220
	s_cmpk_gt_i32 s2, 0xff
	v_readfirstlane_b32 s8, v0
	s_cbranch_scc1 .LBB0_1049
	s_load_dword s10, s[0:1], 0xb0
	v_and_b32_e32 v1, 63, v0
	s_ashr_i32 s8, s8, 6
	v_and_b32_e32 v2, 15, v1
	v_lshrrev_b32_e32 v3, 4, v1
	s_and_b32 s12, s8, 3
	s_lshr_b32 s13, s8, 2
	v_mul_u32_u24_e32 v8, 0x110, v2
	v_lshl_add_u32 v9, v3, 4, v8
	s_mul_i32 s11, s13, 0x1100
	v_add_u32_e32 v9, s11, v9
	v_lshl_add_u32 v8, v3, 3, v8
	s_lshl_b32 s11, s8, 5
	v_add_u32_e32 v8, s11, v8
	v_lshlrev_b32_e32 v10, 4, v1
	v_add_u32_e32 v10, 0x5000, v10
	v_lshlrev_b32_e32 v11, 4, v3
	s_lshl_b32 s11, s8, 6
	s_add_i32 s11, s11, 0xd000
	v_add_u32_e32 v11, s11, v11
	s_mov_b32 s9, s2
	s_mov_b32 s20, 0x8000
	s_mov_b32 s21, 0
	s_mov_b32 s23, 0
	s_mov_b32 s24, 0x40000
	s_mov_b32 s25, 0
	s_mov_b32 s26, 0x4000
	s_mov_b32 s27, 0
	s_waitcnt lgkmcnt(0)
.Lp9_job:
	s_lshr_b32 s11, s9, 3
	s_and_b32 s14, s9, 7
	s_lshl_b32 s14, s14, 1
	s_lshr_b32 s18, s11, 4
	s_add_i32 s14, s14, s18
	s_and_b32 s15, s11, 15
	s_lshr_b32 s16, s14, 2
	s_and_b32 s17, s14, 3
	v_lshlrev_b32_e32 v22, 4, v1
	v_mov_b32_e32 v23, 0
	s_lshl_b32 s18, s14, 21
	s_lshl_b32 s19, s8, 11
	s_add_u32 s18, s18, s19
	s_add_u32 s18, s18, 0x18200000
	s_add_u32 s34, s80, s18
	s_addc_u32 s35, s81, 0
	v_lshl_add_u64 v[12:13], s[34:35], 0, v[22:23]
	s_lshl_b32 s18, s14, 21
	s_lshl_b32 s19, s13, 14
	s_add_u32 s18, s18, s19
	s_lshl_b32 s19, s12, 12
	s_add_u32 s18, s18, s19
	s_add_u32 s18, s18, 0x8200000
	s_add_u32 s34, s80, s18
	s_addc_u32 s35, s81, 0
	v_lshl_add_u64 v[14:15], s[34:35], 0, v[22:23]
	s_lshl_b32 s18, s16, 24
	s_lshl_b32 s19, s13, 17
	s_add_u32 s18, s18, s19
	s_lshl_b32 s19, s12, 15
	s_add_u32 s18, s18, s19
	s_lshl_b32 s19, s17, 9
	s_add_u32 s18, s18, s19
	s_lshl_b32 s19, s15, 5
	s_add_u32 s18, s18, s19
	s_add_u32 s18, s18, 0x1a200000
	s_add_u32 s34, s80, s18
	s_addc_u32 s35, s81, 0
	v_lshlrev_b32_e32 v20, 11, v2
	v_lshl_add_u32 v20, v3, 3, v20
	v_mov_b32_e32 v21, 0
	v_lshl_add_u64 v[20:21], s[34:35], 0, v[20:21]
	s_and_b32 s18, s8, 1
	s_lshl_b32 s18, s18, 10
	s_lshr_b32 s19, s8, 1
	s_lshl_b32 s19, s19, 15
	s_add_u32 s18, s18, s19
	s_lshl_b32 s19, s14, 22
	s_add_u32 s18, s18, s19
	s_lshl_b32 s19, s15, 11
	s_add_u32 s18, s18, s19
	s_add_u32 s18, s18, 0xc200000
	s_lshl_b32 s31, s16, 18
	s_lshl_b32 s19, s17, 9
	s_add_u32 s31, s31, s19
	s_add_u32 s31, s31, 0x3c00000
	s_lshl_b32 s19, s8, 10
	s_add_u32 s19, s19, 0x5000
	s_cmp_lt_u32 s8, 4
	s_cselect_b32 s18, s18, s31
	s_movk_i32 s36, 0x400
	s_movk_i32 s37, 0x1000
	s_cselect_b32 s29, s37, s36
	s_cselect_b32 s22, 0x10000, s37
	s_cselect_b32 s28, s19, 0xd000
	s_cselect_b64 vcc, -1, 0
	s_add_u32 s34, s80, s18
	s_addc_u32 s35, s81, 0
	v_and_b32_e32 v24, 31, v1
	v_lshlrev_b32_e32 v24, 4, v24
	v_lshrrev_b32_e32 v25, 5, v1
	v_lshl_add_u32 v24, v25, 11, v24
	v_cndmask_b32_e32 v16, v24, v22, vcc
	v_mov_b32_e32 v17, 0
	v_lshl_add_u64 v[16:17], s[34:35], 0, v[16:17]
	v_mov_b32_e32 v4, 0
	v_mov_b32_e32 v5, 0
	v_mov_b32_e32 v6, 0
	v_mov_b32_e32 v7, 0
	s_cmp_lt_u32 s8, 5
	s_cbranch_scc0 .Lp9_pnd
	s_mul_i32 s11, s29, 0
	s_add_i32 m0, s28, s11
	s_nop 0
	global_load_lds_dwordx4 v[16:17], off
	v_lshl_add_u64 v[16:17], v[16:17], 0, s[22:23]
	s_mul_i32 s11, s29, 1
	s_add_i32 m0, s28, s11
	s_nop 0
	global_load_lds_dwordx4 v[16:17], off
	v_lshl_add_u64 v[16:17], v[16:17], 0, s[22:23]
	s_mul_i32 s11, s29, 2
	s_add_i32 m0, s28, s11
	s_nop 0
	global_load_lds_dwordx4 v[16:17], off
	v_lshl_add_u64 v[16:17], v[16:17], 0, s[22:23]
	s_mul_i32 s11, s29, 3
	s_add_i32 m0, s28, s11
	s_nop 0
	global_load_lds_dwordx4 v[16:17], off
	v_lshl_add_u64 v[16:17], v[16:17], 0, s[22:23]
	s_mul_i32 s11, s29, 4
	s_add_i32 m0, s28, s11
	s_nop 0
	global_load_lds_dwordx4 v[16:17], off
	v_lshl_add_u64 v[16:17], v[16:17], 0, s[22:23]
.Lp9_pnd:
	v_lshl_add_u64 v[26:27], v[12:13], 0, s[26:27]
	global_load_dwordx4 v[32:35], v[12:13], off
	global_load_dwordx4 v[36:39], v[12:13], off offset:1024
	global_load_dwordx4 v[40:43], v[26:27], off
	global_load_dwordx4 v[44:47], v[26:27], off offset:1024
	v_lshl_add_u64 v[12:13], v[12:13], 0, s[20:21]
	global_load_dwordx4 v[48:51], v[14:15], off
	global_load_dwordx4 v[52:55], v[14:15], off offset:1024
	global_load_dwordx4 v[56:59], v[14:15], off offset:2048
	global_load_dwordx4 v[60:63], v[14:15], off offset:3072
	v_lshl_add_u64 v[14:15], v[14:15], 0, s[20:21]
	v_lshl_add_u64 v[26:27], v[12:13], 0, s[26:27]
	global_load_dwordx4 v[64:67], v[12:13], off
	global_load_dwordx4 v[68:71], v[12:13], off offset:1024
	global_load_dwordx4 v[72:75], v[26:27], off
	global_load_dwordx4 v[76:79], v[26:27], off offset:1024
	v_lshl_add_u64 v[12:13], v[12:13], 0, s[20:21]
	global_load_dwordx4 v[80:83], v[14:15], off
	global_load_dwordx4 v[84:87], v[14:15], off offset:1024
	global_load_dwordx4 v[88:91], v[14:15], off offset:2048
	global_load_dwordx4 v[92:95], v[14:15], off offset:3072
	v_lshl_add_u64 v[14:15], v[14:15], 0, s[20:21]
	v_lshl_add_u64 v[26:27], v[12:13], 0, s[26:27]
	global_load_dwordx4 v[96:99], v[12:13], off
	global_load_dwordx4 v[100:103], v[12:13], off offset:1024
	global_load_dwordx4 v[104:107], v[26:27], off
	global_load_dwordx4 v[108:111], v[26:27], off offset:1024
	v_lshl_add_u64 v[12:13], v[12:13], 0, s[20:21]
	global_load_dwordx4 v[112:115], v[14:15], off
	global_load_dwordx4 v[116:119], v[14:15], off offset:1024
	global_load_dwordx4 v[120:123], v[14:15], off offset:2048
	global_load_dwordx4 v[124:127], v[14:15], off offset:3072
	v_lshl_add_u64 v[14:15], v[14:15], 0, s[20:21]
	v_lshl_add_u64 v[26:27], v[12:13], 0, s[26:27]
	global_load_dwordx4 v[128:131], v[12:13], off
	global_load_dwordx4 v[132:135], v[12:13], off offset:1024
	global_load_dwordx4 v[136:139], v[26:27], off
	global_load_dwordx4 v[140:143], v[26:27], off offset:1024
	v_lshl_add_u64 v[12:13], v[12:13], 0, s[20:21]
	global_load_dwordx4 v[144:147], v[14:15], off
	global_load_dwordx4 v[148:151], v[14:15], off offset:1024
	global_load_dwordx4 v[152:155], v[14:15], off offset:2048
	global_load_dwordx4 v[156:159], v[14:15], off offset:3072
	v_lshl_add_u64 v[14:15], v[14:15], 0, s[20:21]
	s_mov_b32 s30, 0
	s_waitcnt vmcnt(0)
	s_barrier
; #define LAS __attribute__((address_space(3)))
; __device__ __forceinline__ unsigned cvt_pk_bf16(float lo, float hi) { f32x2_t v = {lo, hi}; bf16x2_t b = __builtin_convertvector(v, bf16x2_t); return __builtin_bit_cast(unsigned, b); }
; __device__ __forceinline__ unsigned f2bf(float f) { unsigned u = __builtin_bit_cast(unsigned, f); return (u + 0x7fffu + ((u >> 16) & 1u)) >> 16; }
; template <bool RO>
; __device__ __forceinline__ void p9_job(LAS unsigned char* lds, const bf16_t* __restrict__ kap, const bf16_t* __restrict__ vbp, const float* __restrict__ dcp, const bf16_t* __restrict__ qap, bf16_t* __restrict__ op, int wave, int c16, int kq) {
;     ...
;     for (int c0 = 0; c0 < 128; c0 += PD) {
; #pragma unroll
;         for (int u = 0; u < PD; ++u) {
;             const int c = c0 + u;
;             LAS unsigned char* sl = lds + (u & 1) * P9_SBUF;
; #pragma unroll
;             for (int ct = 0; ct < NCT; ++ct) {
;                 S[ct] = S[ct] * dc[u];
;                 S[ct] = __builtin_amdgcn_mfma_f32_16x16x32_bf16(ka[u][0], vb[u][ct][0], S[ct], 0, 0, 0);
;                 S[ct] = __builtin_amdgcn_mfma_f32_16x16x32_bf16(ka[u][1], vb[u][ct][1], S[ct], 0, 0, 0);
;             }
; #pragma unroll
;             for (int ct = 0; ct < NCT; ++ct) { u32x2 wv; wv.x = cvt_pk_bf16(S[ct][0], S[ct][1]); wv.y = cvt_pk_bf16(S[ct][2], S[ct][3]);
;                 *(LAS u32x2*)(sl + (16 * ct + c16) * 272 + (16 * wave + 4 * kq) * 2) = wv; }
;             asm volatile("s_waitcnt lgkmcnt(0)" ::: "memory"); __builtin_amdgcn_s_barrier(); asm volatile("" ::: "memory");
;             if (RO) {
;                 bf16_t* o2 = op + (size_t)c * 64 * 1024;
; #pragma unroll
;                 for (int ct = 0; ct < NCT; ++ct) {
;                     f32x4 o = (f32x4){0.f, 0.f, 0.f, 0.f};
; #pragma unroll
;                     for (int ks = 0; ks < 4; ++ks) {
;                         const bf16x8 sb = *(const LAS bf16x8*)(sl + (16 * ct + c16) * 272 + (32 * ks + 8 * kq) * 2);
;                         o = __builtin_amdgcn_mfma_f32_16x16x32_bf16(qa[u][ks], sb, o, 0, 0, 0);
;                     }
; #pragma unroll
;                     for (int i = 0; i < 4; ++i) o2[(size_t)i * 1024 + 16 * ct] = (bf16_t)f2bf(o[i]);
;                 }
;             }
;             const int cn = c + PD < 128 ? c + PD : 127;
;             P9_LOAD(u, cn);
;         }
;     }
.Lp9_loop:
	s_waitcnt vmcnt(28)
	s_cmp_lt_u32 s8, 5
	s_cbranch_scc0 .Lp9_nd0
	s_mul_i32 s11, s29, 5
	s_add_i32 m0, s28, s11
	s_nop 0
	global_load_lds_dwordx4 v[16:17], off
	v_lshl_add_u64 v[16:17], v[16:17], 0, s[22:23]
.Lp9_nd0:
	ds_read_b128 v[160:163], v10 offset:0
	ds_read_b128 v[164:167], v10 offset:1024
	ds_read_b128 v[176:179], v11 offset:0
	ds_read_b128 v[168:171], v10 offset:2048
	ds_read_b128 v[172:175], v10 offset:3072
	ds_read_b128 v[180:183], v11 offset:512
	s_waitcnt lgkmcnt(3)
	v_pk_mul_f32 v[4:5], v[4:5], v[176:177]
	v_pk_mul_f32 v[6:7], v[6:7], v[178:179]
	s_nop 1
	v_mfma_f32_16x16x32_bf16 v[4:7], v[32:35], v[160:163], v[4:7]
	v_mfma_f32_16x16x32_bf16 v[4:7], v[36:39], v[164:167], v[4:7]
	s_nop 7
	v_cvt_pk_bf16_f32 v204, v4, v5
	v_cvt_pk_bf16_f32 v205, v6, v7
	ds_write_b64 v8, v[204:205]
	s_waitcnt lgkmcnt(1)
	v_pk_mul_f32 v[4:5], v[4:5], v[180:181]
	v_pk_mul_f32 v[6:7], v[6:7], v[182:183]
	s_nop 1
	v_mfma_f32_16x16x32_bf16 v[4:7], v[40:43], v[168:171], v[4:7]
	v_mfma_f32_16x16x32_bf16 v[4:7], v[44:47], v[172:175], v[4:7]
	v_lshl_add_u64 v[26:27], v[12:13], 0, s[26:27]
	global_load_dwordx4 v[32:35], v[12:13], off
	global_load_dwordx4 v[36:39], v[12:13], off offset:1024
	global_load_dwordx4 v[40:43], v[26:27], off
	global_load_dwordx4 v[44:47], v[26:27], off offset:1024
	v_lshl_add_u64 v[12:13], v[12:13], 0, s[20:21]
	s_nop 1
	v_cvt_pk_bf16_f32 v206, v4, v5
	v_cvt_pk_bf16_f32 v207, v6, v7
	ds_write_b64 v8, v[206:207] offset:4352
	s_waitcnt lgkmcnt(0)
	s_barrier
	ds_read_b128 v[184:187], v9
	ds_read_b128 v[188:191], v9 offset:64
	ds_read_b128 v[192:195], v9 offset:128
	ds_read_b128 v[196:199], v9 offset:192
	s_waitcnt lgkmcnt(3)
	v_mfma_f32_16x16x32_bf16 v[200:203], v[184:187], v[48:51], 0
	s_waitcnt lgkmcnt(2)
	v_mfma_f32_16x16x32_bf16 v[200:203], v[188:191], v[52:55], v[200:203]
	s_waitcnt lgkmcnt(1)
	v_mfma_f32_16x16x32_bf16 v[200:203], v[192:195], v[56:59], v[200:203]
	s_waitcnt lgkmcnt(0)
	v_mfma_f32_16x16x32_bf16 v[200:203], v[196:199], v[60:63], v[200:203]
	global_load_dwordx4 v[48:51], v[14:15], off
	global_load_dwordx4 v[52:55], v[14:15], off offset:1024
	global_load_dwordx4 v[56:59], v[14:15], off offset:2048
	global_load_dwordx4 v[60:63], v[14:15], off offset:3072
	v_lshl_add_u64 v[14:15], v[14:15], 0, s[20:21]
	s_nop 2
	v_cvt_pk_bf16_f32 v208, v200, v201
	v_cvt_pk_bf16_f32 v209, v202, v203
	global_store_dwordx2 v[20:21], v[208:209], off
	v_lshl_add_u64 v[20:21], v[20:21], 0, s[24:25]
	s_waitcnt vmcnt(28)
	s_cmp_lt_u32 s8, 5
	s_cbranch_scc0 .Lp9_nd1
	s_mul_i32 s11, s29, 6
	s_add_i32 m0, s28, s11
	s_nop 0
	global_load_lds_dwordx4 v[16:17], off
	v_lshl_add_u64 v[16:17], v[16:17], 0, s[22:23]
.Lp9_nd1:
	ds_read_b128 v[160:163], v10 offset:4096
	ds_read_b128 v[164:167], v10 offset:5120
	ds_read_b128 v[176:179], v11 offset:1024
	ds_read_b128 v[168:171], v10 offset:6144
	ds_read_b128 v[172:175], v10 offset:7168
	ds_read_b128 v[180:183], v11 offset:1536
	s_waitcnt lgkmcnt(3)
	v_pk_mul_f32 v[4:5], v[4:5], v[176:177]
	v_pk_mul_f32 v[6:7], v[6:7], v[178:179]
	s_nop 1
	v_mfma_f32_16x16x32_bf16 v[4:7], v[64:67], v[160:163], v[4:7]
	v_mfma_f32_16x16x32_bf16 v[4:7], v[68:71], v[164:167], v[4:7]
	s_nop 7
	v_cvt_pk_bf16_f32 v204, v4, v5
	v_cvt_pk_bf16_f32 v205, v6, v7
	ds_write_b64 v8, v[204:205] offset:8704
	s_waitcnt lgkmcnt(1)
	v_pk_mul_f32 v[4:5], v[4:5], v[180:181]
	v_pk_mul_f32 v[6:7], v[6:7], v[182:183]
	s_nop 1
	v_mfma_f32_16x16x32_bf16 v[4:7], v[72:75], v[168:171], v[4:7]
	v_mfma_f32_16x16x32_bf16 v[4:7], v[76:79], v[172:175], v[4:7]
	v_lshl_add_u64 v[26:27], v[12:13], 0, s[26:27]
	global_load_dwordx4 v[64:67], v[12:13], off
	global_load_dwordx4 v[68:71], v[12:13], off offset:1024
	global_load_dwordx4 v[72:75], v[26:27], off
	global_load_dwordx4 v[76:79], v[26:27], off offset:1024
	v_lshl_add_u64 v[12:13], v[12:13], 0, s[20:21]
	s_nop 1
	v_cvt_pk_bf16_f32 v206, v4, v5
	v_cvt_pk_bf16_f32 v207, v6, v7
	ds_write_b64 v8, v[206:207] offset:13056
	s_waitcnt lgkmcnt(0)
	s_barrier
	ds_read_b128 v[184:187], v9 offset:8704
	ds_read_b128 v[188:191], v9 offset:8768
	ds_read_b128 v[192:195], v9 offset:8832
	ds_read_b128 v[196:199], v9 offset:8896
	s_waitcnt lgkmcnt(3)
	v_mfma_f32_16x16x32_bf16 v[200:203], v[184:187], v[80:83], 0
	s_waitcnt lgkmcnt(2)
	v_mfma_f32_16x16x32_bf16 v[200:203], v[188:191], v[84:87], v[200:203]
	s_waitcnt lgkmcnt(1)
	v_mfma_f32_16x16x32_bf16 v[200:203], v[192:195], v[88:91], v[200:203]
	s_waitcnt lgkmcnt(0)
	v_mfma_f32_16x16x32_bf16 v[200:203], v[196:199], v[92:95], v[200:203]
	global_load_dwordx4 v[80:83], v[14:15], off
	global_load_dwordx4 v[84:87], v[14:15], off offset:1024
	global_load_dwordx4 v[88:91], v[14:15], off offset:2048
	global_load_dwordx4 v[92:95], v[14:15], off offset:3072
	v_lshl_add_u64 v[14:15], v[14:15], 0, s[20:21]
	s_nop 2
	v_cvt_pk_bf16_f32 v208, v200, v201
	v_cvt_pk_bf16_f32 v209, v202, v203
	global_store_dwordx2 v[20:21], v[208:209], off
	v_lshl_add_u64 v[20:21], v[20:21], 0, s[24:25]
	s_waitcnt vmcnt(28)
	s_cmp_lt_u32 s8, 5
	s_cbranch_scc0 .Lp9_nd2
	s_mul_i32 s11, s29, 7
	s_add_i32 m0, s28, s11
	s_nop 0
	global_load_lds_dwordx4 v[16:17], off
	v_lshl_add_u64 v[16:17], v[16:17], 0, s[22:23]
; #define LAS __attribute__((address_space(3)))
; __device__ __forceinline__ unsigned cvt_pk_bf16(float lo, float hi) { f32x2_t v = {lo, hi}; bf16x2_t b = __builtin_convertvector(v, bf16x2_t); return __builtin_bit_cast(unsigned, b); }
; __device__ __forceinline__ unsigned f2bf(float f) { unsigned u = __builtin_bit_cast(unsigned, f); return (u + 0x7fffu + ((u >> 16) & 1u)) >> 16; }
; template <bool RO>
; __device__ __forceinline__ void p9_job(LAS unsigned char* lds, const bf16_t* __restrict__ kap, const bf16_t* __restrict__ vbp, const float* __restrict__ dcp, const bf16_t* __restrict__ qap, bf16_t* __restrict__ op, int wave, int c16, int kq) {
;     ...
;     for (int c0 = 0; c0 < 128; c0 += PD) {
; #pragma unroll
;         for (int u = 0; u < PD; ++u) {
;             const int c = c0 + u;
;             LAS unsigned char* sl = lds + (u & 1) * P9_SBUF;
; #pragma unroll
;             for (int ct = 0; ct < NCT; ++ct) {
;                 S[ct] = S[ct] * dc[u];
;                 S[ct] = __builtin_amdgcn_mfma_f32_16x16x32_bf16(ka[u][0], vb[u][ct][0], S[ct], 0, 0, 0);
;                 S[ct] = __builtin_amdgcn_mfma_f32_16x16x32_bf16(ka[u][1], vb[u][ct][1], S[ct], 0, 0, 0);
;             }
; #pragma unroll
;             for (int ct = 0; ct < NCT; ++ct) { u32x2 wv; wv.x = cvt_pk_bf16(S[ct][0], S[ct][1]); wv.y = cvt_pk_bf16(S[ct][2], S[ct][3]);
;                 *(LAS u32x2*)(sl + (16 * ct + c16) * 272 + (16 * wave + 4 * kq) * 2) = wv; }
;             asm volatile("s_waitcnt lgkmcnt(0)" ::: "memory"); __builtin_amdgcn_s_barrier(); asm volatile("" ::: "memory");
;             if (RO) {
;                 bf16_t* o2 = op + (size_t)c * 64 * 1024;
; #pragma unroll
;                 for (int ct = 0; ct < NCT; ++ct) {
;                     f32x4 o = (f32x4){0.f, 0.f, 0.f, 0.f};
; #pragma unroll
;                     for (int ks = 0; ks < 4; ++ks) {
;                         const bf16x8 sb = *(const LAS bf16x8*)(sl + (16 * ct + c16) * 272 + (32 * ks + 8 * kq) * 2);
;                         o = __builtin_amdgcn_mfma_f32_16x16x32_bf16(qa[u][ks], sb, o, 0, 0, 0);
;                     }
; #pragma unroll
;                     for (int i = 0; i < 4; ++i) o2[(size_t)i * 1024 + 16 * ct] = (bf16_t)f2bf(o[i]);
;                 }
;             }
;             const int cn = c + PD < 128 ? c + PD : 127;
;             P9_LOAD(u, cn);
;         }
;     }
.Lp9_nd2:
	ds_read_b128 v[160:163], v10 offset:8192
	ds_read_b128 v[164:167], v10 offset:9216
	ds_read_b128 v[176:179], v11 offset:2048
	ds_read_b128 v[168:171], v10 offset:10240
	ds_read_b128 v[172:175], v10 offset:11264
	ds_read_b128 v[180:183], v11 offset:2560
	s_waitcnt lgkmcnt(3)
	v_pk_mul_f32 v[4:5], v[4:5], v[176:177]
	v_pk_mul_f32 v[6:7], v[6:7], v[178:179]
	s_nop 1
	v_mfma_f32_16x16x32_bf16 v[4:7], v[96:99], v[160:163], v[4:7]
	v_mfma_f32_16x16x32_bf16 v[4:7], v[100:103], v[164:167], v[4:7]
	s_nop 7
	v_cvt_pk_bf16_f32 v204, v4, v5
	v_cvt_pk_bf16_f32 v205, v6, v7
	ds_write_b64 v8, v[204:205]
	s_waitcnt lgkmcnt(1)
	v_pk_mul_f32 v[4:5], v[4:5], v[180:181]
	v_pk_mul_f32 v[6:7], v[6:7], v[182:183]
	s_nop 1
	v_mfma_f32_16x16x32_bf16 v[4:7], v[104:107], v[168:171], v[4:7]
	v_mfma_f32_16x16x32_bf16 v[4:7], v[108:111], v[172:175], v[4:7]
	v_lshl_add_u64 v[26:27], v[12:13], 0, s[26:27]
	global_load_dwordx4 v[96:99], v[12:13], off
	global_load_dwordx4 v[100:103], v[12:13], off offset:1024
	global_load_dwordx4 v[104:107], v[26:27], off
	global_load_dwordx4 v[108:111], v[26:27], off offset:1024
	v_lshl_add_u64 v[12:13], v[12:13], 0, s[20:21]
	s_nop 1
	v_cvt_pk_bf16_f32 v206, v4, v5
	v_cvt_pk_bf16_f32 v207, v6, v7
	ds_write_b64 v8, v[206:207] offset:4352
	s_waitcnt lgkmcnt(0)
	s_barrier
	ds_read_b128 v[184:187], v9
	ds_read_b128 v[188:191], v9 offset:64
	ds_read_b128 v[192:195], v9 offset:128
	ds_read_b128 v[196:199], v9 offset:192
	s_waitcnt lgkmcnt(3)
	v_mfma_f32_16x16x32_bf16 v[200:203], v[184:187], v[112:115], 0
	s_waitcnt lgkmcnt(2)
	v_mfma_f32_16x16x32_bf16 v[200:203], v[188:191], v[116:119], v[200:203]
	s_waitcnt lgkmcnt(1)
	v_mfma_f32_16x16x32_bf16 v[200:203], v[192:195], v[120:123], v[200:203]
	s_waitcnt lgkmcnt(0)
	v_mfma_f32_16x16x32_bf16 v[200:203], v[196:199], v[124:127], v[200:203]
	global_load_dwordx4 v[112:115], v[14:15], off
	global_load_dwordx4 v[116:119], v[14:15], off offset:1024
	global_load_dwordx4 v[120:123], v[14:15], off offset:2048
	global_load_dwordx4 v[124:127], v[14:15], off offset:3072
	v_lshl_add_u64 v[14:15], v[14:15], 0, s[20:21]
	s_nop 2
	v_cvt_pk_bf16_f32 v208, v200, v201
	v_cvt_pk_bf16_f32 v209, v202, v203
	global_store_dwordx2 v[20:21], v[208:209], off
	v_lshl_add_u64 v[20:21], v[20:21], 0, s[24:25]
	s_waitcnt vmcnt(28)
	s_cmp_lt_u32 s8, 5
	s_cbranch_scc0 .Lp9_nd3
	s_mul_i32 s11, s29, 0
	s_add_i32 m0, s28, s11
	s_nop 0
	global_load_lds_dwordx4 v[16:17], off
	v_lshl_add_u64 v[16:17], v[16:17], 0, s[22:23]
.Lp9_nd3:
	ds_read_b128 v[160:163], v10 offset:12288
	ds_read_b128 v[164:167], v10 offset:13312
	ds_read_b128 v[176:179], v11 offset:3072
	ds_read_b128 v[168:171], v10 offset:14336
	ds_read_b128 v[172:175], v10 offset:15360
	ds_read_b128 v[180:183], v11 offset:3584
	s_waitcnt lgkmcnt(3)
	v_pk_mul_f32 v[4:5], v[4:5], v[176:177]
	v_pk_mul_f32 v[6:7], v[6:7], v[178:179]
	s_nop 1
	v_mfma_f32_16x16x32_bf16 v[4:7], v[128:131], v[160:163], v[4:7]
	v_mfma_f32_16x16x32_bf16 v[4:7], v[132:135], v[164:167], v[4:7]
	s_nop 7
	v_cvt_pk_bf16_f32 v204, v4, v5
	v_cvt_pk_bf16_f32 v205, v6, v7
	ds_write_b64 v8, v[204:205] offset:8704
	s_waitcnt lgkmcnt(1)
	v_pk_mul_f32 v[4:5], v[4:5], v[180:181]
	v_pk_mul_f32 v[6:7], v[6:7], v[182:183]
	s_nop 1
	v_mfma_f32_16x16x32_bf16 v[4:7], v[136:139], v[168:171], v[4:7]
	v_mfma_f32_16x16x32_bf16 v[4:7], v[140:143], v[172:175], v[4:7]
	v_lshl_add_u64 v[26:27], v[12:13], 0, s[26:27]
	global_load_dwordx4 v[128:131], v[12:13], off
	global_load_dwordx4 v[132:135], v[12:13], off offset:1024
	global_load_dwordx4 v[136:139], v[26:27], off
	global_load_dwordx4 v[140:143], v[26:27], off offset:1024
	v_lshl_add_u64 v[12:13], v[12:13], 0, s[20:21]
	s_nop 1
	v_cvt_pk_bf16_f32 v206, v4, v5
	v_cvt_pk_bf16_f32 v207, v6, v7
	ds_write_b64 v8, v[206:207] offset:13056
	s_waitcnt lgkmcnt(0)
	s_barrier
	ds_read_b128 v[184:187], v9 offset:8704
	ds_read_b128 v[188:191], v9 offset:8768
	ds_read_b128 v[192:195], v9 offset:8832
	ds_read_b128 v[196:199], v9 offset:8896
	s_waitcnt lgkmcnt(3)
	v_mfma_f32_16x16x32_bf16 v[200:203], v[184:187], v[144:147], 0
	s_waitcnt lgkmcnt(2)
	v_mfma_f32_16x16x32_bf16 v[200:203], v[188:191], v[148:151], v[200:203]
	s_waitcnt lgkmcnt(1)
	v_mfma_f32_16x16x32_bf16 v[200:203], v[192:195], v[152:155], v[200:203]
	s_waitcnt lgkmcnt(0)
	v_mfma_f32_16x16x32_bf16 v[200:203], v[196:199], v[156:159], v[200:203]
	global_load_dwordx4 v[144:147], v[14:15], off
	global_load_dwordx4 v[148:151], v[14:15], off offset:1024
	global_load_dwordx4 v[152:155], v[14:15], off offset:2048
	global_load_dwordx4 v[156:159], v[14:15], off offset:3072
	v_lshl_add_u64 v[14:15], v[14:15], 0, s[20:21]
	s_nop 2
	v_cvt_pk_bf16_f32 v208, v200, v201
	v_cvt_pk_bf16_f32 v209, v202, v203
	global_store_dwordx2 v[20:21], v[208:209], off
	v_lshl_add_u64 v[20:21], v[20:21], 0, s[24:25]
	s_waitcnt vmcnt(28)
	s_cmp_lt_u32 s8, 5
	s_cbranch_scc0 .Lp9_nd4
	s_mul_i32 s11, s29, 1
	s_add_i32 m0, s28, s11
	s_nop 0
	global_load_lds_dwordx4 v[16:17], off
	v_lshl_add_u64 v[16:17], v[16:17], 0, s[22:23]
; #define LAS __attribute__((address_space(3)))
; __device__ __forceinline__ unsigned cvt_pk_bf16(float lo, float hi) { f32x2_t v = {lo, hi}; bf16x2_t b = __builtin_convertvector(v, bf16x2_t); return __builtin_bit_cast(unsigned, b); }
; __device__ __forceinline__ unsigned f2bf(float f) { unsigned u = __builtin_bit_cast(unsigned, f); return (u + 0x7fffu + ((u >> 16) & 1u)) >> 16; }
; template <bool RO>
; __device__ __forceinline__ void p9_job(LAS unsigned char* lds, const bf16_t* __restrict__ kap, const bf16_t* __restrict__ vbp, const float* __restrict__ dcp, const bf16_t* __restrict__ qap, bf16_t* __restrict__ op, int wave, int c16, int kq) {
;     ...
;     for (int c0 = 0; c0 < 128; c0 += PD) {
; #pragma unroll
;         for (int u = 0; u < PD; ++u) {
;             const int c = c0 + u;
;             LAS unsigned char* sl = lds + (u & 1) * P9_SBUF;
; #pragma unroll
;             for (int ct = 0; ct < NCT; ++ct) {
;                 S[ct] = S[ct] * dc[u];
;                 S[ct] = __builtin_amdgcn_mfma_f32_16x16x32_bf16(ka[u][0], vb[u][ct][0], S[ct], 0, 0, 0);
;                 S[ct] = __builtin_amdgcn_mfma_f32_16x16x32_bf16(ka[u][1], vb[u][ct][1], S[ct], 0, 0, 0);
;             }
; #pragma unroll
;             for (int ct = 0; ct < NCT; ++ct) { u32x2 wv; wv.x = cvt_pk_bf16(S[ct][0], S[ct][1]); wv.y = cvt_pk_bf16(S[ct][2], S[ct][3]);
;                 *(LAS u32x2*)(sl + (16 * ct + c16) * 272 + (16 * wave + 4 * kq) * 2) = wv; }
;             asm volatile("s_waitcnt lgkmcnt(0)" ::: "memory"); __builtin_amdgcn_s_barrier(); asm volatile("" ::: "memory");
;             if (RO) {
;                 bf16_t* o2 = op + (size_t)c * 64 * 1024;
; #pragma unroll
;                 for (int ct = 0; ct < NCT; ++ct) {
;                     f32x4 o = (f32x4){0.f, 0.f, 0.f, 0.f};
; #pragma unroll
;                     for (int ks = 0; ks < 4; ++ks) {
;                         const bf16x8 sb = *(const LAS bf16x8*)(sl + (16 * ct + c16) * 272 + (32 * ks + 8 * kq) * 2);
;                         o = __builtin_amdgcn_mfma_f32_16x16x32_bf16(qa[u][ks], sb, o, 0, 0, 0);
;                     }
; #pragma unroll
;                     for (int i = 0; i < 4; ++i) o2[(size_t)i * 1024 + 16 * ct] = (bf16_t)f2bf(o[i]);
;                 }
;             }
;             const int cn = c + PD < 128 ? c + PD : 127;
;             P9_LOAD(u, cn);
;         }
;     }
.Lp9_nd4:
	ds_read_b128 v[160:163], v10 offset:16384
	ds_read_b128 v[164:167], v10 offset:17408
	ds_read_b128 v[176:179], v11 offset:4096
	ds_read_b128 v[168:171], v10 offset:18432
	ds_read_b128 v[172:175], v10 offset:19456
	ds_read_b128 v[180:183], v11 offset:4608
	s_waitcnt lgkmcnt(3)
	v_pk_mul_f32 v[4:5], v[4:5], v[176:177]
	v_pk_mul_f32 v[6:7], v[6:7], v[178:179]
	s_nop 1
	v_mfma_f32_16x16x32_bf16 v[4:7], v[32:35], v[160:163], v[4:7]
	v_mfma_f32_16x16x32_bf16 v[4:7], v[36:39], v[164:167], v[4:7]
	s_nop 7
	v_cvt_pk_bf16_f32 v204, v4, v5
	v_cvt_pk_bf16_f32 v205, v6, v7
	ds_write_b64 v8, v[204:205]
	s_waitcnt lgkmcnt(1)
	v_pk_mul_f32 v[4:5], v[4:5], v[180:181]
	v_pk_mul_f32 v[6:7], v[6:7], v[182:183]
	s_nop 1
	v_mfma_f32_16x16x32_bf16 v[4:7], v[40:43], v[168:171], v[4:7]
	v_mfma_f32_16x16x32_bf16 v[4:7], v[44:47], v[172:175], v[4:7]
	v_lshl_add_u64 v[26:27], v[12:13], 0, s[26:27]
	global_load_dwordx4 v[32:35], v[12:13], off
	global_load_dwordx4 v[36:39], v[12:13], off offset:1024
	global_load_dwordx4 v[40:43], v[26:27], off
	global_load_dwordx4 v[44:47], v[26:27], off offset:1024
	v_lshl_add_u64 v[12:13], v[12:13], 0, s[20:21]
	s_nop 1
	v_cvt_pk_bf16_f32 v206, v4, v5
	v_cvt_pk_bf16_f32 v207, v6, v7
	ds_write_b64 v8, v[206:207] offset:4352
	s_waitcnt lgkmcnt(0)
	s_barrier
	ds_read_b128 v[184:187], v9
	ds_read_b128 v[188:191], v9 offset:64
	ds_read_b128 v[192:195], v9 offset:128
	ds_read_b128 v[196:199], v9 offset:192
	s_waitcnt lgkmcnt(3)
	v_mfma_f32_16x16x32_bf16 v[200:203], v[184:187], v[48:51], 0
	s_waitcnt lgkmcnt(2)
	v_mfma_f32_16x16x32_bf16 v[200:203], v[188:191], v[52:55], v[200:203]
	s_waitcnt lgkmcnt(1)
	v_mfma_f32_16x16x32_bf16 v[200:203], v[192:195], v[56:59], v[200:203]
	s_waitcnt lgkmcnt(0)
	v_mfma_f32_16x16x32_bf16 v[200:203], v[196:199], v[60:63], v[200:203]
	global_load_dwordx4 v[48:51], v[14:15], off
	global_load_dwordx4 v[52:55], v[14:15], off offset:1024
	global_load_dwordx4 v[56:59], v[14:15], off offset:2048
	global_load_dwordx4 v[60:63], v[14:15], off offset:3072
	v_lshl_add_u64 v[14:15], v[14:15], 0, s[20:21]
	s_nop 2
	v_cvt_pk_bf16_f32 v208, v200, v201
	v_cvt_pk_bf16_f32 v209, v202, v203
	global_store_dwordx2 v[20:21], v[208:209], off
	v_lshl_add_u64 v[20:21], v[20:21], 0, s[24:25]
	s_waitcnt vmcnt(28)
	s_cmp_lt_u32 s8, 5
	s_cbranch_scc0 .Lp9_nd5
	s_mul_i32 s11, s29, 2
	s_add_i32 m0, s28, s11
	s_nop 0
	global_load_lds_dwordx4 v[16:17], off
	v_lshl_add_u64 v[16:17], v[16:17], 0, s[22:23]
.Lp9_nd5:
	ds_read_b128 v[160:163], v10 offset:20480
	ds_read_b128 v[164:167], v10 offset:21504
	ds_read_b128 v[176:179], v11 offset:5120
	ds_read_b128 v[168:171], v10 offset:22528
	ds_read_b128 v[172:175], v10 offset:23552
	ds_read_b128 v[180:183], v11 offset:5632
	s_waitcnt lgkmcnt(3)
	v_pk_mul_f32 v[4:5], v[4:5], v[176:177]
	v_pk_mul_f32 v[6:7], v[6:7], v[178:179]
	s_nop 1
	v_mfma_f32_16x16x32_bf16 v[4:7], v[64:67], v[160:163], v[4:7]
	v_mfma_f32_16x16x32_bf16 v[4:7], v[68:71], v[164:167], v[4:7]
	s_nop 7
	v_cvt_pk_bf16_f32 v204, v4, v5
	v_cvt_pk_bf16_f32 v205, v6, v7
	ds_write_b64 v8, v[204:205] offset:8704
	s_waitcnt lgkmcnt(1)
	v_pk_mul_f32 v[4:5], v[4:5], v[180:181]
	v_pk_mul_f32 v[6:7], v[6:7], v[182:183]
	s_nop 1
	v_mfma_f32_16x16x32_bf16 v[4:7], v[72:75], v[168:171], v[4:7]
	v_mfma_f32_16x16x32_bf16 v[4:7], v[76:79], v[172:175], v[4:7]
	v_lshl_add_u64 v[26:27], v[12:13], 0, s[26:27]
	global_load_dwordx4 v[64:67], v[12:13], off
	global_load_dwordx4 v[68:71], v[12:13], off offset:1024
	global_load_dwordx4 v[72:75], v[26:27], off
	global_load_dwordx4 v[76:79], v[26:27], off offset:1024
	v_lshl_add_u64 v[12:13], v[12:13], 0, s[20:21]
	s_nop 1
	v_cvt_pk_bf16_f32 v206, v4, v5
	v_cvt_pk_bf16_f32 v207, v6, v7
	ds_write_b64 v8, v[206:207] offset:13056
	s_waitcnt lgkmcnt(0)
	s_barrier
	ds_read_b128 v[184:187], v9 offset:8704
	ds_read_b128 v[188:191], v9 offset:8768
	ds_read_b128 v[192:195], v9 offset:8832
	ds_read_b128 v[196:199], v9 offset:8896
	s_waitcnt lgkmcnt(3)
	v_mfma_f32_16x16x32_bf16 v[200:203], v[184:187], v[80:83], 0
	s_waitcnt lgkmcnt(2)
	v_mfma_f32_16x16x32_bf16 v[200:203], v[188:191], v[84:87], v[200:203]
	s_waitcnt lgkmcnt(1)
	v_mfma_f32_16x16x32_bf16 v[200:203], v[192:195], v[88:91], v[200:203]
	s_waitcnt lgkmcnt(0)
	v_mfma_f32_16x16x32_bf16 v[200:203], v[196:199], v[92:95], v[200:203]
	global_load_dwordx4 v[80:83], v[14:15], off
	global_load_dwordx4 v[84:87], v[14:15], off offset:1024
	global_load_dwordx4 v[88:91], v[14:15], off offset:2048
	global_load_dwordx4 v[92:95], v[14:15], off offset:3072
	v_lshl_add_u64 v[14:15], v[14:15], 0, s[20:21]
	s_nop 2
	v_cvt_pk_bf16_f32 v208, v200, v201
	v_cvt_pk_bf16_f32 v209, v202, v203
	global_store_dwordx2 v[20:21], v[208:209], off
	v_lshl_add_u64 v[20:21], v[20:21], 0, s[24:25]
	s_waitcnt vmcnt(28)
	s_cmp_lt_u32 s8, 5
	s_cbranch_scc0 .Lp9_nd6
	s_mul_i32 s11, s29, 3
	s_add_i32 m0, s28, s11
	s_nop 0
	global_load_lds_dwordx4 v[16:17], off
	v_lshl_add_u64 v[16:17], v[16:17], 0, s[22:23]
; #define LAS __attribute__((address_space(3)))
; template <bool RO>
; __device__ __forceinline__ void p9_job(LAS unsigned char* lds, const bf16_t* __restrict__ kap, const bf16_t* __restrict__ vbp, const float* __restrict__ dcp, const bf16_t* __restrict__ qap, bf16_t* __restrict__ op, int wave, int c16, int kq) {
;     ...
;     for (int c0 = 0; c0 < 128; c0 += PD) {
; #pragma unroll
;         for (int u = 0; u < PD; ++u) {
;             const int c = c0 + u;
;             LAS unsigned char* sl = lds + (u & 1) * P9_SBUF;
; #pragma unroll
;             for (int ct = 0; ct < NCT; ++ct) {
;                 S[ct] = S[ct] * dc[u];
;                 S[ct] = __builtin_amdgcn_mfma_f32_16x16x32_bf16(ka[u][0], vb[u][ct][0], S[ct], 0, 0, 0);
;                 S[ct] = __builtin_amdgcn_mfma_f32_16x16x32_bf16(ka[u][1], vb[u][ct][1], S[ct], 0, 0, 0);
;             }
; #pragma unroll
;             for (int ct = 0; ct < NCT; ++ct) { u32x2 wv; wv.x = cvt_pk_bf16(S[ct][0], S[ct][1]); wv.y = cvt_pk_bf16(S[ct][2], S[ct][3]);
;                 *(LAS u32x2*)(sl + (16 * ct + c16) * 272 + (16 * wave + 4 * kq) * 2) = wv; }
;             asm volatile("s_waitcnt lgkmcnt(0)" ::: "memory"); __builtin_amdgcn_s_barrier(); asm volatile("" ::: "memory");
;             if (RO) {
;                 bf16_t* o2 = op + (size_t)c * 64 * 1024;
; #pragma unroll
;                 for (int ct = 0; ct < NCT; ++ct) {
;                     f32x4 o = (f32x4){0.f, 0.f, 0.f, 0.f};
; #pragma unroll
;                     for (int ks = 0; ks < 4; ++ks) {
;                         const bf16x8 sb = *(const LAS bf16x8*)(sl + (16 * ct + c16) * 272 + (32 * ks + 8 * kq) * 2);
;                         o = __builtin_amdgcn_mfma_f32_16x16x32_bf16(qa[u][ks], sb, o, 0, 0, 0);
;                     }
; #pragma unroll
;                     for (int i = 0; i < 4; ++i) o2[(size_t)i * 1024 + 16 * ct] = (bf16_t)f2bf(o[i]);
;                 }
;             }
;             const int cn = c + PD < 128 ? c + PD : 127;
;             P9_LOAD(u, cn);
;         }
;     }
; __global__ void __launch_bounds__(512, 2) hybrid_fwd(Args args) {
;     ...
;         for (int jb = blk; jb < 16 * (16 / P9_NCT); jb += G) {
;             constexpr int JPB = 16 / P9_NCT;
;             const int idx = jb >> 3, bh = 2 * (jb & 7) + idx / JPB, dvs = idx % JPB;
;             const int b = bh >> 2, h = bh & 3;
;             const int c16 = lane & 15, kq = lane >> 4;
.Lp9_nd6:
	ds_read_b128 v[160:163], v10 offset:24576
	ds_read_b128 v[164:167], v10 offset:25600
	ds_read_b128 v[176:179], v11 offset:6144
	ds_read_b128 v[168:171], v10 offset:26624
	ds_read_b128 v[172:175], v10 offset:27648
	ds_read_b128 v[180:183], v11 offset:6656
	s_waitcnt lgkmcnt(3)
	v_pk_mul_f32 v[4:5], v[4:5], v[176:177]
	v_pk_mul_f32 v[6:7], v[6:7], v[178:179]
	s_nop 1
	v_mfma_f32_16x16x32_bf16 v[4:7], v[96:99], v[160:163], v[4:7]
	v_mfma_f32_16x16x32_bf16 v[4:7], v[100:103], v[164:167], v[4:7]
	s_nop 7
	v_cvt_pk_bf16_f32 v204, v4, v5
	v_cvt_pk_bf16_f32 v205, v6, v7
	ds_write_b64 v8, v[204:205]
	s_waitcnt lgkmcnt(1)
	v_pk_mul_f32 v[4:5], v[4:5], v[180:181]
	v_pk_mul_f32 v[6:7], v[6:7], v[182:183]
	s_nop 1
	v_mfma_f32_16x16x32_bf16 v[4:7], v[104:107], v[168:171], v[4:7]
	v_mfma_f32_16x16x32_bf16 v[4:7], v[108:111], v[172:175], v[4:7]
	v_lshl_add_u64 v[26:27], v[12:13], 0, s[26:27]
	global_load_dwordx4 v[96:99], v[12:13], off
	global_load_dwordx4 v[100:103], v[12:13], off offset:1024
	global_load_dwordx4 v[104:107], v[26:27], off
	global_load_dwordx4 v[108:111], v[26:27], off offset:1024
	v_lshl_add_u64 v[12:13], v[12:13], 0, s[20:21]
	s_nop 1
	v_cvt_pk_bf16_f32 v206, v4, v5
	v_cvt_pk_bf16_f32 v207, v6, v7
	ds_write_b64 v8, v[206:207] offset:4352
	s_waitcnt lgkmcnt(0)
	s_barrier
	ds_read_b128 v[184:187], v9
	ds_read_b128 v[188:191], v9 offset:64
	ds_read_b128 v[192:195], v9 offset:128
	ds_read_b128 v[196:199], v9 offset:192
	s_waitcnt lgkmcnt(3)
	v_mfma_f32_16x16x32_bf16 v[200:203], v[184:187], v[112:115], 0
	s_waitcnt lgkmcnt(2)
	v_mfma_f32_16x16x32_bf16 v[200:203], v[188:191], v[116:119], v[200:203]
	s_waitcnt lgkmcnt(1)
	v_mfma_f32_16x16x32_bf16 v[200:203], v[192:195], v[120:123], v[200:203]
	s_waitcnt lgkmcnt(0)
	v_mfma_f32_16x16x32_bf16 v[200:203], v[196:199], v[124:127], v[200:203]
	global_load_dwordx4 v[112:115], v[14:15], off
	global_load_dwordx4 v[116:119], v[14:15], off offset:1024
	global_load_dwordx4 v[120:123], v[14:15], off offset:2048
	global_load_dwordx4 v[124:127], v[14:15], off offset:3072
	v_lshl_add_u64 v[14:15], v[14:15], 0, s[20:21]
	s_nop 2
	v_cvt_pk_bf16_f32 v208, v200, v201
	v_cvt_pk_bf16_f32 v209, v202, v203
	global_store_dwordx2 v[20:21], v[208:209], off
	v_lshl_add_u64 v[20:21], v[20:21], 0, s[24:25]
	s_waitcnt vmcnt(28)
	s_cmp_lt_u32 s8, 5
	s_cbranch_scc0 .Lp9_nd7
	s_mul_i32 s11, s29, 4
	s_add_i32 m0, s28, s11
	s_nop 0
	global_load_lds_dwordx4 v[16:17], off
	v_lshl_add_u64 v[16:17], v[16:17], 0, s[22:23]
.Lp9_nd7:
	ds_read_b128 v[160:163], v10 offset:28672
	ds_read_b128 v[164:167], v10 offset:29696
	ds_read_b128 v[176:179], v11 offset:7168
	ds_read_b128 v[168:171], v10 offset:30720
	ds_read_b128 v[172:175], v10 offset:31744
	ds_read_b128 v[180:183], v11 offset:7680
	s_waitcnt lgkmcnt(3)
	v_pk_mul_f32 v[4:5], v[4:5], v[176:177]
	v_pk_mul_f32 v[6:7], v[6:7], v[178:179]
	s_nop 1
	v_mfma_f32_16x16x32_bf16 v[4:7], v[128:131], v[160:163], v[4:7]
	v_mfma_f32_16x16x32_bf16 v[4:7], v[132:135], v[164:167], v[4:7]
	s_nop 7
	v_cvt_pk_bf16_f32 v204, v4, v5
	v_cvt_pk_bf16_f32 v205, v6, v7
	ds_write_b64 v8, v[204:205] offset:8704
	s_waitcnt lgkmcnt(1)
	v_pk_mul_f32 v[4:5], v[4:5], v[180:181]
	v_pk_mul_f32 v[6:7], v[6:7], v[182:183]
	s_nop 1
	v_mfma_f32_16x16x32_bf16 v[4:7], v[136:139], v[168:171], v[4:7]
	v_mfma_f32_16x16x32_bf16 v[4:7], v[140:143], v[172:175], v[4:7]
	v_lshl_add_u64 v[26:27], v[12:13], 0, s[26:27]
	global_load_dwordx4 v[128:131], v[12:13], off
	global_load_dwordx4 v[132:135], v[12:13], off offset:1024
	global_load_dwordx4 v[136:139], v[26:27], off
	global_load_dwordx4 v[140:143], v[26:27], off offset:1024
	v_lshl_add_u64 v[12:13], v[12:13], 0, s[20:21]
	s_nop 1
	v_cvt_pk_bf16_f32 v206, v4, v5
	v_cvt_pk_bf16_f32 v207, v6, v7
	ds_write_b64 v8, v[206:207] offset:13056
	s_waitcnt lgkmcnt(0)
	s_barrier
	ds_read_b128 v[184:187], v9 offset:8704
	ds_read_b128 v[188:191], v9 offset:8768
	ds_read_b128 v[192:195], v9 offset:8832
	ds_read_b128 v[196:199], v9 offset:8896
	s_waitcnt lgkmcnt(3)
	v_mfma_f32_16x16x32_bf16 v[200:203], v[184:187], v[144:147], 0
	s_waitcnt lgkmcnt(2)
	v_mfma_f32_16x16x32_bf16 v[200:203], v[188:191], v[148:151], v[200:203]
	s_waitcnt lgkmcnt(1)
	v_mfma_f32_16x16x32_bf16 v[200:203], v[192:195], v[152:155], v[200:203]
	s_waitcnt lgkmcnt(0)
	v_mfma_f32_16x16x32_bf16 v[200:203], v[196:199], v[156:159], v[200:203]
	global_load_dwordx4 v[144:147], v[14:15], off
	global_load_dwordx4 v[148:151], v[14:15], off offset:1024
	global_load_dwordx4 v[152:155], v[14:15], off offset:2048
	global_load_dwordx4 v[156:159], v[14:15], off offset:3072
	v_lshl_add_u64 v[14:15], v[14:15], 0, s[20:21]
	s_nop 2
	v_cvt_pk_bf16_f32 v208, v200, v201
	v_cvt_pk_bf16_f32 v209, v202, v203
	global_store_dwordx2 v[20:21], v[208:209], off
	v_lshl_add_u64 v[20:21], v[20:21], 0, s[24:25]
	s_add_i32 s30, s30, 1
	s_cmp_lt_u32 s30, 8
	s_cbranch_scc1 .Lp9_loop
	s_add_i32 s9, s9, s10
	s_cmpk_lt_i32 s9, 0x100
	s_waitcnt vmcnt(0) lgkmcnt(0)
	s_barrier
	s_cbranch_scc1 .Lp9_job
